# v61 + nt on the mLSTM chunk-state (P2) and scan (P3) stores
# baseline (speedup 1.0000x reference)
.Lp2_pf_none:
	s_and_saveexec_b64 s[46:47], s[14:15]
	s_cbranch_execz .Lp2_ml_skip
	s_ashr_i32 s43, s42, 31
	s_lshl_b64 s[48:49], s[42:43], 2
	s_add_u32 s76, s50, s48
	s_addc_u32 s77, s51, s49
	s_add_u32 s48, s52, s48
	s_addc_u32 s49, s53, s49
	global_store_dword v85, v234, s[76:77] nt
	global_store_dword v85, v235, s[48:49] nt
.Lp2_ml_skip:
	s_or_b64 exec, exec, s[46:47]
	s_bfe_u32 s46, s64, 0x20006
	s_ashr_i32 s44, s64, 8
	s_mul_i32 s43, s46, 3
	s_mul_i32 s34, s46, 0x60
	v_add_u32_e32 v28, s34, v96
	s_add_i32 s34, s43, 1
	s_mul_i32 s45, s44, 0xc0
	s_add_i32 s43, s43, 2
	v_lshl_add_u32 v36, s34, 5, v96
	v_add_u32_e32 v84, s45, v96
	v_lshl_add_u32 v48, s43, 5, v96
	s_waitcnt lgkmcnt(0)
	s_barrier
	ds_read_b64_tr_b16 v[0:1], v28 offset:25600
	ds_read_b64_tr_b16 v[2:3], v28 offset:27200
	ds_read_b64_tr_b16 v[6:7], v84 offset:1600
	ds_read_b64_tr_b16 v[4:5], v84
	ds_read_b64_tr_b16 v[8:9], v36 offset:25600
	ds_read_b64_tr_b16 v[10:11], v36 offset:27200
	ds_read_b64_tr_b16 v[12:13], v84 offset:32
	ds_read_b64_tr_b16 v[16:17], v84 offset:64
	ds_read_b64_tr_b16 v[20:21], v84 offset:96
	ds_read_b64_tr_b16 v[14:15], v84 offset:1632
	ds_read_b64_tr_b16 v[24:25], v84 offset:160
	ds_read_b64_tr_b16 v[30:31], v28 offset:40000
	ds_read_b64_tr_b16 v[38:39], v36 offset:40000
	ds_read_b64_tr_b16 v[44:45], v48 offset:25600
	ds_read_b64_tr_b16 v[46:47], v48 offset:27200
	ds_read_b64_tr_b16 v[50:51], v48 offset:40000
	ds_read_b64_tr_b16 v[18:19], v84 offset:1664
	ds_read_b64_tr_b16 v[22:23], v84 offset:1696
	ds_read_b64_tr_b16 v[62:63], v84 offset:1728
	ds_read_b64_tr_b16 v[26:27], v84 offset:1760
	ds_read_b64_tr_b16 v[60:61], v84 offset:128
	ds_read_b64_tr_b16 v[28:29], v28 offset:38400
	ds_read_b64_tr_b16 v[36:37], v36 offset:38400
	ds_read_b64_tr_b16 v[48:49], v48 offset:38400
	s_waitcnt lgkmcnt(14)
	v_mfma_f32_16x16x32_bf16 v[32:35], v[4:7], v[0:3], 0
	ds_read_b64_tr_b16 v[130:131], v84 offset:12800
	ds_read_b64_tr_b16 v[134:135], v84 offset:12832
	ds_read_b64_tr_b16 v[138:139], v84 offset:12864
	ds_read_b64_tr_b16 v[142:143], v84 offset:12896
	ds_read_b64_tr_b16 v[132:133], v84 offset:14400
	ds_read_b64_tr_b16 v[136:137], v84 offset:14432
	ds_read_b64_tr_b16 v[146:147], v84 offset:12928
	ds_read_b64_tr_b16 v[150:151], v84 offset:12960
	s_mul_i32 s46, s46, 48
	v_mfma_f32_16x16x32_bf16 v[40:43], v[4:7], v[8:11], 0
	s_mul_i32 s47, s44, 6
	ds_read_b64_tr_b16 v[140:141], v84 offset:14464
	ds_read_b64_tr_b16 v[144:145], v84 offset:14496
	ds_read_b64_tr_b16 v[148:149], v84 offset:14528
	ds_read_b64_tr_b16 v[152:153], v84 offset:14560
	v_or_b32_e32 v84, s47, v97
	s_waitcnt lgkmcnt(14)
	v_mfma_f32_16x16x32_bf16 v[4:7], v[4:7], v[44:47], 0
	s_mul_i32 s44, s42, 0x12000
	v_lshlrev_b32_e32 v84, 4, v84
	s_mul_hi_i32 s45, s42, 0x12000
	v_mfma_f32_16x16x32_bf16 v[52:55], v[12:15], v[0:3], 0
	s_add_u32 s44, s26, s44
	s_addc_u32 s45, s27, s45
	v_mfma_f32_16x16x32_bf16 v[56:59], v[12:15], v[8:11], 0
	v_mfma_f32_16x16x32_bf16 v[12:15], v[12:15], v[44:47], 0
	v_mfma_f32_16x16x32_bf16 v[64:67], v[16:19], v[0:3], 0
	v_mfma_f32_16x16x32_bf16 v[110:113], v[16:19], v[8:11], 0
	v_mfma_f32_16x16x32_bf16 v[16:19], v[16:19], v[44:47], 0
	v_mfma_f32_16x16x32_bf16 v[114:117], v[20:23], v[0:3], 0
	v_mfma_f32_16x16x32_bf16 v[118:121], v[20:23], v[8:11], 0
	v_mfma_f32_16x16x32_bf16 v[20:23], v[20:23], v[44:47], 0
	v_mfma_f32_16x16x32_bf16 v[122:125], v[60:63], v[0:3], 0
	v_mfma_f32_16x16x32_bf16 v[126:129], v[60:63], v[8:11], 0
	v_mfma_f32_16x16x32_bf16 v[60:63], v[60:63], v[44:47], 0
	v_mfma_f32_16x16x32_bf16 v[0:3], v[24:27], v[0:3], 0
	v_mfma_f32_16x16x32_bf16 v[8:11], v[24:27], v[8:11], 0
	v_mfma_f32_16x16x32_bf16 v[24:27], v[24:27], v[44:47], 0
	v_or_b32_e32 v44, s46, v90
	v_mul_u32_u24_e32 v44, 0xc0, v44
	s_waitcnt lgkmcnt(7)
	v_mfma_f32_16x16x32_bf16 v[32:35], v[130:133], v[28:31], v[32:35]
	v_mfma_f32_16x16x32_bf16 v[40:43], v[130:133], v[36:39], v[40:43]
	v_mfma_f32_16x16x32_bf16 v[4:7], v[130:133], v[48:51], v[4:7]
	v_or_b32_e32 v130, v44, v98
	s_nop 4
	v_cvt_pk_bf16_f32 v32, v32, v33
	v_cvt_pk_bf16_f32 v33, v34, v35
	s_waitcnt lgkmcnt(6)
	v_mfma_f32_16x16x32_bf16 v[44:47], v[134:137], v[28:31], v[52:55]
	v_cvt_pk_bf16_f32 v40, v40, v41
	v_cvt_pk_bf16_f32 v41, v42, v43
	s_waitcnt lgkmcnt(3)
	v_mfma_f32_16x16x32_bf16 v[52:55], v[138:141], v[28:31], v[64:67]
	s_nop 2
	v_add_u32_e32 v66, 32, v84
	v_cvt_pk_bf16_f32 v34, v44, v45
	v_cvt_pk_bf16_f32 v35, v46, v47
	v_mfma_f32_16x16x32_bf16 v[44:47], v[134:137], v[36:39], v[56:59]
	v_permlane16_swap_b32_e32 v32, v34
	v_permlane16_swap_b32_e32 v33, v35
	s_nop 0
	v_add_u32_e32 v56, v130, v84
	v_ashrrev_i32_e32 v57, 31, v56
	v_lshl_add_u64 v[56:57], v[56:57], 1, s[44:45]
	global_store_dwordx4 v[56:57], v[32:35], off nt
	s_waitcnt lgkmcnt(2)
	v_mfma_f32_16x16x32_bf16 v[56:59], v[142:145], v[28:31], v[114:117]
	v_add_u32_e32 v64, v130, v66
	v_cvt_pk_bf16_f32 v32, v52, v53
	v_cvt_pk_bf16_f32 v33, v54, v55
	v_ashrrev_i32_e32 v65, 31, v64
	s_waitcnt lgkmcnt(0)
	v_mfma_f32_16x16x32_bf16 v[0:3], v[150:153], v[28:31], v[0:3]
	s_nop 1
	v_cvt_pk_bf16_f32 v34, v56, v57
	v_cvt_pk_bf16_f32 v35, v58, v59
	s_nop 0
	v_permlane16_swap_b32_e32 v32, v34
	v_mfma_f32_16x16x32_bf16 v[56:59], v[146:149], v[28:31], v[122:125]
	v_permlane16_swap_b32_e32 v33, v35
	v_lshl_add_u64 v[64:65], v[64:65], 1, s[44:45]
	global_store_dwordx4 v[64:65], v[32:35], off nt
	v_mfma_f32_16x16x32_bf16 v[52:55], v[138:141], v[36:39], v[110:113]
	v_cvt_pk_bf16_f32 v42, v44, v45
	s_nop 2
	v_cvt_pk_bf16_f32 v33, v58, v59
	v_add_u32_e32 v58, 64, v84
	v_cvt_pk_bf16_f32 v32, v56, v57
	v_add_u32_e32 v56, v130, v58
	v_cvt_pk_bf16_f32 v34, v0, v1
	v_cvt_pk_bf16_f32 v35, v2, v3
	v_ashrrev_i32_e32 v57, 31, v56
	v_permlane16_swap_b32_e32 v32, v34
	v_permlane16_swap_b32_e32 v33, v35
	v_lshl_add_u64 v[56:57], v[56:57], 1, s[44:45]
	global_store_dwordx4 v[56:57], v[32:35], off nt
	v_lshl_or_b32 v56, s34, 4, v90
	v_mfma_f32_16x16x32_bf16 v[0:3], v[142:145], v[36:39], v[118:121]
	v_mul_u32_u24_e32 v56, 0xc0, v56
	v_or_b32_e32 v56, v56, v98
	v_cvt_pk_bf16_f32 v43, v46, v47
	v_mfma_f32_16x16x32_bf16 v[28:31], v[146:149], v[36:39], v[126:129]
	v_permlane16_swap_b32_e32 v40, v42
	v_permlane16_swap_b32_e32 v41, v43
	v_mfma_f32_16x16x32_bf16 v[8:11], v[150:153], v[36:39], v[8:11]
	v_add_u32_e32 v36, v56, v84
	v_ashrrev_i32_e32 v37, 31, v36
	v_lshl_add_u64 v[36:37], v[36:37], 1, s[44:45]
	v_cvt_pk_bf16_f32 v38, v0, v1
	v_add_u32_e32 v0, v56, v66
	global_store_dwordx4 v[36:37], v[40:43], off nt
	v_cvt_pk_bf16_f32 v36, v52, v53
	v_cvt_pk_bf16_f32 v37, v54, v55
	v_cvt_pk_bf16_f32 v39, v2, v3
	v_ashrrev_i32_e32 v1, 31, v0
	v_permlane16_swap_b32_e32 v36, v38
	v_permlane16_swap_b32_e32 v37, v39
	v_lshl_add_u64 v[0:1], v[0:1], 1, s[44:45]
	v_cvt_pk_bf16_f32 v2, v8, v9
	v_add_u32_e32 v8, v56, v58
	global_store_dwordx4 v[0:1], v[36:39], off nt
	v_cvt_pk_bf16_f32 v0, v28, v29
	v_cvt_pk_bf16_f32 v1, v30, v31
	v_cvt_pk_bf16_f32 v3, v10, v11
	v_ashrrev_i32_e32 v9, 31, v8
	v_permlane16_swap_b32_e32 v0, v2
	v_permlane16_swap_b32_e32 v1, v3
	v_lshl_add_u64 v[8:9], v[8:9], 1, s[44:45]
	v_mfma_f32_16x16x32_bf16 v[12:15], v[134:137], v[48:51], v[12:15]
	global_store_dwordx4 v[8:9], v[0:3], off nt
	s_nop 1
	v_lshl_or_b32 v0, s43, 4, v90
	v_mul_u32_u24_e32 v0, 0xc0, v0
	v_or_b32_e32 v8, v0, v98
	v_mfma_f32_16x16x32_bf16 v[16:19], v[138:141], v[48:51], v[16:19]
	v_cvt_pk_bf16_f32 v0, v4, v5
	v_add_u32_e32 v4, v8, v84
	v_cvt_pk_bf16_f32 v1, v6, v7
	v_mfma_f32_16x16x32_bf16 v[20:23], v[142:145], v[48:51], v[20:23]
	v_cvt_pk_bf16_f32 v2, v12, v13
	v_cvt_pk_bf16_f32 v3, v14, v15
	v_ashrrev_i32_e32 v5, 31, v4
	v_permlane16_swap_b32_e32 v0, v2
	v_permlane16_swap_b32_e32 v1, v3
	v_lshl_add_u64 v[4:5], v[4:5], 1, s[44:45]
	v_mfma_f32_16x16x32_bf16 v[32:35], v[146:149], v[48:51], v[60:63]
	global_store_dwordx4 v[4:5], v[0:3], off nt
	v_add_u32_e32 v4, v8, v66
	v_ashrrev_i32_e32 v5, 31, v4
	v_mfma_f32_16x16x32_bf16 v[24:27], v[150:153], v[48:51], v[24:27]
	v_cvt_pk_bf16_f32 v0, v16, v17
	v_cvt_pk_bf16_f32 v1, v18, v19
	v_cvt_pk_bf16_f32 v2, v20, v21
	v_cvt_pk_bf16_f32 v3, v22, v23
	s_nop 0
	v_permlane16_swap_b32_e32 v0, v2
	v_permlane16_swap_b32_e32 v1, v3
	v_lshl_add_u64 v[4:5], v[4:5], 1, s[44:45]
	global_store_dwordx4 v[4:5], v[0:3], off nt
	v_add_u32_e32 v4, v8, v58
	v_ashrrev_i32_e32 v5, 31, v4
	v_cvt_pk_bf16_f32 v0, v32, v33
	v_cvt_pk_bf16_f32 v1, v34, v35
	v_cvt_pk_bf16_f32 v2, v24, v25
	v_cvt_pk_bf16_f32 v3, v26, v27
	s_nop 0
	v_permlane16_swap_b32_e32 v0, v2
	v_permlane16_swap_b32_e32 v1, v3
	v_lshl_add_u64 v[4:5], v[4:5], 1, s[44:45]
	global_store_dwordx4 v[4:5], v[0:3], off nt
	s_and_saveexec_b64 s[44:45], s[18:19]
	s_cbranch_execz .LBB0_285
	v_mov_b32_e32 v0, 0
	s_mov_b32 s34, -2
	v_mov_b32_e32 v2, v99
	v_mov_b32_e32 v1, v0
.LBB0_307:
	ds_read_u16 v3, v2 offset:400
	ds_read_u16 v6, v2 offset:1200
	ds_read_u16 v8, v2 offset:2000
	ds_read_u16 v10, v2 offset:2800
	ds_read_u16 v11, v2 offset:2400
	ds_read_u16 v9, v2 offset:1600
	ds_read_u16 v7, v2 offset:800
	ds_read_u16 v4, v2
	ds_read_u16 v12, v2 offset:3600
	ds_read_u16 v14, v2 offset:4400
	ds_read_u16 v16, v2 offset:5200
	ds_read_u16 v18, v2 offset:6000
	ds_read_u16 v19, v2 offset:5600
	ds_read_u16 v17, v2 offset:4800
	ds_read_u16 v15, v2 offset:4000
	ds_read_u16 v13, v2 offset:3200
	s_waitcnt lgkmcnt(8)
	v_lshlrev_b32_e32 v5, 16, v4
	v_lshlrev_b32_e32 v4, 16, v3
	v_lshlrev_b32_e32 v7, 16, v7
	v_lshlrev_b32_e32 v6, 16, v6
	v_pk_add_f32 v[0:1], v[0:1], v[4:5]
	v_lshlrev_b32_e32 v9, 16, v9
	v_lshlrev_b32_e32 v8, 16, v8
	v_pk_add_f32 v[0:1], v[0:1], v[6:7]
	v_lshlrev_b32_e32 v11, 16, v11
	v_lshlrev_b32_e32 v10, 16, v10
	v_pk_add_f32 v[0:1], v[0:1], v[8:9]
	s_waitcnt lgkmcnt(0)
	v_lshlrev_b32_e32 v13, 16, v13
	v_lshlrev_b32_e32 v12, 16, v12
	v_pk_add_f32 v[0:1], v[0:1], v[10:11]
	v_lshlrev_b32_e32 v15, 16, v15
	v_lshlrev_b32_e32 v14, 16, v14
	v_pk_add_f32 v[0:1], v[0:1], v[12:13]
	v_lshlrev_b32_e32 v17, 16, v17
	v_lshlrev_b32_e32 v16, 16, v16
	v_pk_add_f32 v[0:1], v[0:1], v[14:15]
	s_add_i32 s34, s34, 16
	v_lshlrev_b32_e32 v19, 16, v19
	v_lshlrev_b32_e32 v18, 16, v18
	v_pk_add_f32 v[0:1], v[0:1], v[16:17]
	v_add_u32_e32 v2, 0x1900, v2
	s_cmp_gt_u32 s34, 61
	v_pk_add_f32 v[0:1], v[0:1], v[18:19]
	s_cbranch_scc0 .LBB0_307
	v_add_f32_e32 v2, v1, v0
	v_mad_i64_i32 v[0:1], s[46:47], s42, v93, v[82:83]
	global_store_dword v[0:1], v2, off nt
	s_branch .LBB0_285

.LBB0_311:
	v_cndmask_b32_e64 v10, v10, v91, s[0:1]
	v_sub_f32_e32 v10, 0, v10
	v_fmamk_f32 v12, v68, 0x3e38aa3b, v10
	v_exp_f32_e32 v12, v12
	v_fmamk_f32 v13, v69, 0x3e38aa3b, v10
	v_exp_f32_e32 v13, v13
	v_fmamk_f32 v14, v70, 0x3e38aa3b, v10
	v_exp_f32_e32 v14, v14
	v_fmamk_f32 v68, v71, 0x3e38aa3b, v10
	v_exp_f32_e32 v68, v68
	v_fmamk_f32 v64, v64, 0x3e38aa3b, v10
	v_add_f32_e32 v15, 0, v12
	v_exp_f32_e32 v64, v64
	v_fmamk_f32 v65, v65, 0x3e38aa3b, v10
	v_add_f32_e32 v15, v13, v15
	v_exp_f32_e32 v65, v65
	v_fmamk_f32 v66, v66, 0x3e38aa3b, v10
	v_add_f32_e32 v15, v14, v15
	v_exp_f32_e32 v66, v66
	v_fmamk_f32 v67, v67, 0x3e38aa3b, v10
	v_add_f32_e32 v15, v68, v15
	v_exp_f32_e32 v67, v67
	v_fmamk_f32 v60, v60, 0x3e38aa3b, v10
	v_add_f32_e32 v15, v64, v15
	v_exp_f32_e32 v60, v60
	v_fmamk_f32 v61, v61, 0x3e38aa3b, v10
	v_add_f32_e32 v15, v65, v15
	v_exp_f32_e32 v61, v61
	v_fmamk_f32 v62, v62, 0x3e38aa3b, v10
	v_add_f32_e32 v15, v66, v15
	v_exp_f32_e32 v62, v62
	v_fmamk_f32 v63, v63, 0x3e38aa3b, v10
	v_add_f32_e32 v15, v67, v15
	v_exp_f32_e32 v63, v63
	v_fmamk_f32 v4, v4, 0x3e38aa3b, v10
	v_add_f32_e32 v15, v60, v15
	v_exp_f32_e32 v69, v4
	v_fmamk_f32 v4, v5, 0x3e38aa3b, v10
	v_add_f32_e32 v15, v61, v15
	v_exp_f32_e32 v70, v4
	v_fmamk_f32 v4, v6, 0x3e38aa3b, v10
	v_cndmask_b32_e32 v11, v11, v72, vcc
	v_add_f32_e32 v15, v62, v15
	v_exp_f32_e32 v71, v4
	v_fmac_f32_e32 v10, 0x3e38aa3b, v7
	v_sub_f32_e32 v11, 0, v11
	v_add_f32_e32 v4, v63, v15
	v_exp_f32_e32 v10, v10
	v_fmamk_f32 v56, v56, 0x3e38aa3b, v11
	v_add_f32_e32 v4, v69, v4
	v_exp_f32_e32 v72, v56
	v_fmamk_f32 v56, v57, 0x3e38aa3b, v11
	v_add_f32_e32 v4, v70, v4
	v_exp_f32_e32 v74, v56
	v_fmamk_f32 v56, v58, 0x3e38aa3b, v11
	v_fmamk_f32 v20, v20, 0x3e38aa3b, v11
	v_add_f32_e32 v73, v71, v4
	v_exp_f32_e32 v75, v56
	v_fmamk_f32 v56, v59, 0x3e38aa3b, v11
	v_exp_f32_e32 v77, v20
	v_fmamk_f32 v20, v21, 0x3e38aa3b, v11
	v_cvt_pk_bf16_f32 v15, v71, v10
	v_exp_f32_e32 v76, v56
	v_exp_f32_e32 v78, v20
	v_fmamk_f32 v20, v22, 0x3e38aa3b, v11
	v_add_f32_e32 v10, v10, v73
	v_exp_f32_e32 v79, v20
	v_fmamk_f32 v20, v23, 0x3e38aa3b, v11
	v_add_f32_e32 v8, v10, v8
	v_add_f32_e32 v10, 0, v72
	v_exp_f32_e32 v80, v20
	ds_read_b64_tr_b16 v[22:23], v119 offset:29952
	ds_read_b64_tr_b16 v[20:21], v119 offset:27648
	v_add_f32_e32 v10, v74, v10
	v_add_f32_e32 v10, v75, v10
	v_fmamk_f32 v16, v16, 0x3e38aa3b, v11
	v_add_f32_e32 v10, v76, v10
	v_cvt_pk_bf16_f32 v4, v12, v13
	v_cvt_pk_bf16_f32 v5, v14, v68
	v_cvt_pk_bf16_f32 v6, v64, v65
	v_cvt_pk_bf16_f32 v7, v66, v67
	v_cvt_pk_bf16_f32 v12, v60, v61
	v_cvt_pk_bf16_f32 v13, v62, v63
	v_cvt_pk_bf16_f32 v14, v69, v70
	ds_read_b64_tr_b16 v[60:61], v119 offset:27680
	ds_read_b64_tr_b16 v[64:65], v119 offset:27712
	ds_read_b64_tr_b16 v[68:69], v119 offset:27744
	ds_read_b64_tr_b16 v[62:63], v119 offset:29984
	ds_read_b64_tr_b16 v[66:67], v119 offset:30016
	ds_read_b64_tr_b16 v[70:71], v119 offset:30048
	v_exp_f32_e32 v81, v16
	v_fmamk_f32 v16, v17, 0x3e38aa3b, v11
	v_add_f32_e32 v10, v77, v10
	v_cvt_pk_bf16_f32 v56, v72, v74
	v_cvt_pk_bf16_f32 v57, v75, v76
	v_cvt_pk_bf16_f32 v58, v77, v78
	v_cvt_pk_bf16_f32 v59, v79, v80
	v_exp_f32_e32 v82, v16
	v_fmamk_f32 v16, v18, 0x3e38aa3b, v11
	v_add_f32_e32 v10, v78, v10
	s_waitcnt lgkmcnt(6)
	v_mfma_f32_16x16x32_bf16 v[48:51], v[20:23], v[4:7], v[48:51]
	v_exp_f32_e32 v83, v16
	v_add_f32_e32 v10, v79, v10
	v_fmamk_f32 v0, v0, 0x3e38aa3b, v11
	v_mfma_f32_16x16x32_bf16 v[20:23], v[20:23], v[56:59], v[52:55]
	v_add_f32_e32 v10, v80, v10
	v_add_f32_e32 v10, v81, v10
	v_add_f32_e32 v10, v82, v10
	v_fmamk_f32 v52, v19, 0x3e38aa3b, v11
	s_waitcnt lgkmcnt(2)
	v_mfma_f32_16x16x32_bf16 v[44:47], v[60:63], v[4:7], v[44:47]
	v_add_f32_e32 v10, v83, v10
	v_mov_b32_e32 v117, v99
	v_mov_b32_e32 v113, v99
	v_mfma_f32_16x16x32_bf16 v[16:19], v[60:63], v[56:59], v[40:43]
	v_exp_f32_e32 v60, v52
	v_exp_f32_e32 v61, v0
	v_fmamk_f32 v0, v1, 0x3e38aa3b, v11
	v_exp_f32_e32 v62, v0
	v_fmamk_f32 v0, v2, 0x3e38aa3b, v11
	v_fmac_f32_e32 v11, 0x3e38aa3b, v3
	s_waitcnt lgkmcnt(1)
	v_mfma_f32_16x16x32_bf16 v[36:39], v[64:67], v[4:7], v[36:39]
	v_exp_f32_e32 v63, v0
	v_exp_f32_e32 v11, v11
	v_add_f32_e32 v10, v60, v10
	v_mfma_f32_16x16x32_bf16 v[32:35], v[64:67], v[56:59], v[32:35]
	v_add_f32_e32 v10, v61, v10
	v_add_f32_e32 v10, v62, v10
	v_add_f32_e32 v10, v63, v10
	s_waitcnt lgkmcnt(0)
	v_mfma_f32_16x16x32_bf16 v[0:3], v[68:71], v[4:7], v[28:31]
	ds_read_b64_tr_b16 v[4:5], v119 offset:32256
	ds_read_b64_tr_b16 v[6:7], v119 offset:34560
	s_add_i32 s20, s20, s90
	v_cvt_pk_bf16_f32 v28, v81, v82
	v_mfma_f32_16x16x32_bf16 v[24:27], v[68:71], v[56:59], v[24:27]
	ds_read_b64_tr_b16 v[40:41], v119 offset:32288
	ds_read_b64_tr_b16 v[52:53], v119 offset:32320
	ds_read_b64_tr_b16 v[56:57], v119 offset:32352
	ds_read_b64_tr_b16 v[42:43], v119 offset:34592
	ds_read_b64_tr_b16 v[54:55], v119 offset:34624
	ds_read_b64_tr_b16 v[58:59], v119 offset:34656
	v_cvt_pk_bf16_f32 v29, v83, v60
	v_cvt_pk_bf16_f32 v30, v61, v62
	v_cvt_pk_bf16_f32 v31, v63, v11
	s_waitcnt lgkmcnt(6)
	v_mfma_f32_16x16x32_bf16 v[48:51], v[4:7], v[12:15], v[48:51]
	s_add_i32 s14, s14, s15
	s_cmpk_lt_i32 s20, 0x200
	v_mfma_f32_16x16x32_bf16 v[4:7], v[4:7], v[28:31], v[20:23]
	s_waitcnt lgkmcnt(2)
	v_mfma_f32_16x16x32_bf16 v[20:23], v[40:43], v[12:15], v[44:47]
	s_waitcnt lgkmcnt(1)
	v_mfma_f32_16x16x32_bf16 v[36:39], v[52:55], v[12:15], v[36:39]
	s_waitcnt lgkmcnt(0)
	v_mfma_f32_16x16x32_bf16 v[0:3], v[56:59], v[12:15], v[0:3]
	v_add_f32_e32 v14, v11, v10
	v_add_f32_e32 v15, v14, v9
	v_mov_b32_e32 v9, v8
	s_nop 1
	v_permlane16_swap_b32_e32 v8, v9
	v_add_f32_e32 v8, v8, v9
	v_mov_b32_e32 v9, v8
	s_nop 1
	v_permlane32_swap_b32_e32 v8, v9
	v_add_f32_e32 v14, v8, v9
	v_mfma_f32_16x16x32_bf16 v[10:13], v[56:59], v[28:31], v[24:27]
	v_lshl_add_u64 v[8:9], s[6:7], 0, v[98:99]
	v_lshl_add_u64 v[8:9], v[8:9], 0, v[116:117]
	v_lshl_add_u64 v[8:9], v[8:9], 0, v[112:113]
	v_div_scale_f32 v24, s[0:1], v14, v14, 1.0
	v_rcp_f32_e32 v25, v24
	v_mfma_f32_16x16x32_bf16 v[16:19], v[40:43], v[28:31], v[16:19]
	v_fma_f32 v26, -v24, v25, 1.0
	v_fmac_f32_e32 v25, v26, v25
	v_div_scale_f32 v26, vcc, 1.0, v14, 1.0
	v_mul_f32_e32 v27, v26, v25
	v_mfma_f32_16x16x32_bf16 v[32:35], v[52:55], v[28:31], v[32:35]
	v_fma_f32 v28, -v24, v27, v26
	v_fmac_f32_e32 v27, v28, v25
	v_fma_f32 v24, -v24, v27, v26
	v_div_fmas_f32 v24, v24, v25, v27
	v_div_fixup_f32 v14, v24, v14, 1.0
	v_pk_mul_f32 v[24:25], v[48:49], v[14:15] op_sel_hi:[1,0]
	v_pk_mul_f32 v[26:27], v[50:51], v[14:15] op_sel_hi:[1,0]
	v_pk_mul_f32 v[20:21], v[20:21], v[14:15] op_sel_hi:[1,0]
	v_cvt_pk_bf16_f32 v24, v24, v25
	v_cvt_pk_bf16_f32 v25, v26, v27
	v_cvt_pk_bf16_f32 v26, v20, v21
	v_pk_mul_f32 v[20:21], v[22:23], v[14:15] op_sel_hi:[1,0]
	v_pk_mul_f32 v[22:23], v[38:39], v[14:15] op_sel_hi:[1,0]
	v_cvt_pk_bf16_f32 v27, v20, v21
	v_pk_mul_f32 v[20:21], v[36:37], v[14:15] op_sel_hi:[1,0]
	v_pk_mul_f32 v[0:1], v[0:1], v[14:15] op_sel_hi:[1,0]
	v_cvt_pk_bf16_f32 v20, v20, v21
	v_cvt_pk_bf16_f32 v21, v22, v23
	v_cvt_pk_bf16_f32 v22, v0, v1
	v_pk_mul_f32 v[0:1], v[2:3], v[14:15] op_sel_hi:[1,0]
	s_nop 0
	v_permlane16_swap_b32_e32 v20, v22
	v_cvt_pk_bf16_f32 v23, v0, v1
	v_mov_b32_e32 v0, v15
	s_nop 1
	v_permlane16_swap_b32_e32 v15, v0
	v_add_f32_e32 v0, v15, v0
	v_mov_b32_e32 v1, v0
	s_nop 1
	v_permlane32_swap_b32_e32 v0, v1
	v_add_f32_e32 v0, v0, v1
	v_div_scale_f32 v1, s[0:1], v0, v0, 1.0
	v_rcp_f32_e32 v2, v1
	v_permlane16_swap_b32_e32 v21, v23
	v_permlane16_swap_b32_e32 v24, v26
	v_fma_f32 v3, -v1, v2, 1.0
	v_fmac_f32_e32 v2, v3, v2
	v_div_scale_f32 v3, vcc, 1.0, v0, 1.0
	v_mul_f32_e32 v14, v3, v2
	v_fma_f32 v15, -v1, v14, v3
	v_fmac_f32_e32 v14, v15, v2
	v_fma_f32 v1, -v1, v14, v3
	v_div_fmas_f32 v1, v1, v2, v14
	v_div_fixup_f32 v14, v1, v0, 1.0
	v_pk_mul_f32 v[0:1], v[4:5], v[14:15] op_sel_hi:[1,0]
	v_pk_mul_f32 v[2:3], v[6:7], v[14:15] op_sel_hi:[1,0]
	v_cvt_pk_bf16_f32 v0, v0, v1
	v_cvt_pk_bf16_f32 v1, v2, v3
	v_pk_mul_f32 v[2:3], v[16:17], v[14:15] op_sel_hi:[1,0]
	v_pk_mul_f32 v[4:5], v[18:19], v[14:15] op_sel_hi:[1,0]
	v_cvt_pk_bf16_f32 v2, v2, v3
	v_cvt_pk_bf16_f32 v3, v4, v5
	v_add_co_u32_e32 v4, vcc, s16, v8
	v_permlane16_swap_b32_e32 v0, v2
	v_permlane16_swap_b32_e32 v1, v3
	v_addc_co_u32_e32 v5, vcc, 0, v9, vcc
	global_store_dwordx4 v[4:5], v[0:3], off nt
	v_pk_mul_f32 v[4:5], v[12:13], v[14:15] op_sel_hi:[1,0]
	v_permlane16_swap_b32_e32 v25, v27
	v_pk_mul_f32 v[0:1], v[32:33], v[14:15] op_sel_hi:[1,0]
	v_pk_mul_f32 v[2:3], v[34:35], v[14:15] op_sel_hi:[1,0]
	v_cvt_pk_bf16_f32 v0, v0, v1
	v_cvt_pk_bf16_f32 v1, v2, v3
	v_pk_mul_f32 v[2:3], v[10:11], v[14:15] op_sel_hi:[1,0]
	global_store_dwordx4 v[8:9], v[20:23], off offset:64 nt
	v_cvt_pk_bf16_f32 v2, v2, v3
	v_cvt_pk_bf16_f32 v3, v4, v5
	v_lshl_add_u64 v[20:21], v[8:9], 0, s[4:5]
	v_permlane16_swap_b32_e32 v0, v2
	v_permlane16_swap_b32_e32 v1, v3
	global_store_dwordx4 v[8:9], v[24:27], off nt
	global_store_dwordx4 v[20:21], v[0:3], off offset:64 nt
	s_cbranch_scc0 .LBB0_324

.LBB0_381:
	v_lshl_add_u64 v[6:7], s[88:89], 0, v[2:3]
	v_add_co_u32_e32 v10, vcc, 0x3f00000, v6
	v_lshl_add_u64 v[8:9], s[88:89], 0, v[0:1]
	s_nop 0
	v_addc_co_u32_e32 v11, vcc, 0, v7, vcc
	v_add_co_u32_e32 v6, vcc, 0x3f02000, v6
	s_add_i32 s36, s36, -4
	s_nop 0
	v_addc_co_u32_e32 v7, vcc, 0, v7, vcc
	global_load_dword v12, v[10:11], off
	global_load_dword v13, v[6:7], off
	v_add_co_u32_e32 v8, vcc, 0x3d00000, v8
	v_lshl_add_u64 v[0:1], v[0:1], 0, s[10:11]
	s_nop 0
	v_addc_co_u32_e32 v9, vcc, 0, v9, vcc
	global_load_dword v14, v[8:9], off
	v_lshl_add_u64 v[2:3], v[2:3], 0, 16
	global_store_dword v[8:9], v4, off nt
	global_load_dword v15, v[6:7], off offset:4
	global_load_dword v16, v[10:11], off offset:4
	global_load_dword v17, v[8:9], off offset:768
	s_cmp_lg_u32 s36, 0
	s_waitcnt vmcnt(0)
	v_max_f32_e32 v18, v12, v12
	v_add_f32_e32 v5, v5, v13
	v_max_f32_e32 v13, v5, v18
	v_sub_f32_e32 v12, v12, v13
	v_sub_f32_e32 v5, v5, v13
	v_mul_f32_e32 v12, 0x3fb8aa3b, v12
	v_mul_f32_e32 v5, 0x3fb8aa3b, v5
	v_exp_f32_e32 v12, v12
	v_add_f32_e32 v13, v13, v15
	v_max_f32_e32 v15, v16, v16
	v_max_f32_e32 v15, v13, v15
	v_exp_f32_e32 v5, v5
	v_sub_f32_e32 v16, v16, v15
	v_sub_f32_e32 v13, v13, v15
	v_mul_f32_e32 v16, 0x3fb8aa3b, v16
	v_mul_f32_e32 v13, 0x3fb8aa3b, v13
	v_exp_f32_e32 v16, v16
	v_exp_f32_e32 v13, v13
	v_mul_f32_e32 v12, v14, v12
	v_fmac_f32_e32 v12, v4, v5
	global_store_dword v[8:9], v12, off offset:768 nt
	v_mul_f32_e32 v4, v17, v16
	global_load_dword v5, v[6:7], off offset:8
	global_load_dword v14, v[10:11], off offset:8
	v_fmac_f32_e32 v4, v12, v13
	global_load_dword v12, v[8:9], off offset:1536
	s_waitcnt vmcnt(2)
	v_add_f32_e32 v5, v15, v5
	global_store_dword v[8:9], v4, off offset:1536 nt
	global_load_dword v6, v[6:7], off offset:12
	s_nop 0
	global_load_dword v7, v[10:11], off offset:12
	s_nop 0
	global_load_dword v10, v[8:9], off offset:2304
	s_waitcnt vmcnt(5)
	v_max_f32_e32 v11, v14, v14
	v_max_f32_e32 v11, v5, v11
	v_sub_f32_e32 v5, v5, v11
	v_sub_f32_e32 v13, v14, v11
	v_mul_f32_e32 v14, 0x3fb8aa3b, v5
	v_mul_f32_e32 v13, 0x3fb8aa3b, v13
	v_exp_f32_e32 v13, v13
	s_waitcnt vmcnt(2)
	v_add_f32_e32 v6, v11, v6
	s_waitcnt vmcnt(1)
	v_max_f32_e32 v11, v7, v7
	v_max_f32_e32 v5, v6, v11
	v_sub_f32_e32 v7, v7, v5
	v_sub_f32_e32 v6, v6, v5
	v_mul_f32_e32 v7, 0x3fb8aa3b, v7
	v_exp_f32_e32 v11, v14
	v_mul_f32_e32 v6, 0x3fb8aa3b, v6
	v_exp_f32_e32 v7, v7
	v_exp_f32_e32 v6, v6
	v_mul_f32_e32 v12, v12, v13
	v_fmac_f32_e32 v12, v4, v11
	s_waitcnt vmcnt(0)
	v_mul_f32_e32 v4, v10, v7
	v_fmac_f32_e32 v4, v12, v6
	global_store_dword v[8:9], v12, off offset:2304 nt
	s_cbranch_scc1 .LBB0_381

.LBB0_385:
	v_lshl_add_u64 v[40:41], s[88:89], 0, v[36:37]
	v_add_co_u32_e32 v56, vcc, 0x16000000, v40
	v_lshl_add_u64 v[42:43], s[88:89], 0, v[34:35]
	s_nop 0
	v_addc_co_u32_e32 v57, vcc, 0, v41, vcc
	v_add_co_u32_e32 v0, vcc, 0x16012000, v40
	v_cvt_pk_bf16_f32 v60, v48, v49
	s_nop 0
	v_addc_co_u32_e32 v1, vcc, 0, v41, vcc
	global_load_dwordx4 v[28:31], v[56:57], off
	global_load_dwordx4 v[24:27], v[0:1], off
	v_add_co_u32_e32 v0, vcc, 0x16024000, v40
	v_cvt_pk_bf16_f32 v61, v50, v51
	s_nop 0
	v_addc_co_u32_e32 v1, vcc, 0, v41, vcc
	v_add_co_u32_e32 v2, vcc, 0x16036000, v40
	v_cvt_pk_bf16_f32 v62, v54, v55
	s_nop 0
	v_addc_co_u32_e32 v3, vcc, 0, v41, vcc
	global_load_dwordx4 v[20:23], v[0:1], off
	global_load_dwordx4 v[16:19], v[2:3], off
	v_add_co_u32_e32 v0, vcc, 0x16048000, v40
	v_cvt_pk_bf16_f32 v63, v52, v53
	s_nop 0
	v_addc_co_u32_e32 v1, vcc, 0, v41, vcc
	v_add_co_u32_e32 v2, vcc, 0x1605a000, v40
	s_nop 1
	v_addc_co_u32_e32 v3, vcc, 0, v41, vcc
	global_load_dwordx4 v[12:15], v[0:1], off
	global_load_dwordx4 v[8:11], v[2:3], off
	v_add_co_u32_e32 v0, vcc, 0x1606c000, v40
	s_nop 1
	v_addc_co_u32_e32 v1, vcc, 0, v41, vcc
	v_add_co_u32_e32 v2, vcc, 0x1607e000, v40
	s_nop 1
	v_addc_co_u32_e32 v3, vcc, 0, v41, vcc
	v_add_co_u32_e32 v44, vcc, s43, v42
	global_load_dwordx4 v[4:7], v[0:1], off
	s_nop 0
	global_load_dwordx4 v[0:3], v[2:3], off
	v_addc_co_u32_e32 v45, vcc, 0, v43, vcc
	v_add_co_u32_e32 v46, vcc, s44, v42
	s_nop 1
	v_addc_co_u32_e32 v47, vcc, 0, v43, vcc
	global_load_dword v58, v[44:45], off
	global_load_dword v59, v[46:47], off
	s_nop 0
	global_store_dwordx4 v[56:57], v[60:63], off nt
	s_and_saveexec_b64 s[38:39], s[0:1]
	s_cbranch_execz .LBB0_387
	v_add_co_u32_e32 v56, vcc, 0x3f04000, v42
	s_nop 1
	v_addc_co_u32_e32 v57, vcc, 0, v43, vcc
	global_store_dword v[56:57], v32, off nt
.LBB0_387:
	s_or_b64 exec, exec, s[38:39]
	global_load_dword v56, v[44:45], off offset:4
	global_load_dword v57, v[46:47], off offset:4
	s_waitcnt vmcnt(0)
	v_add_f32_e32 v59, v32, v59
	v_max_f32_e32 v32, v58, v58
	v_max_f32_e32 v32, v59, v32
	v_sub_f32_e32 v58, v58, v32
	v_sub_f32_e32 v59, v59, v32
	v_mul_f32_e32 v58, 0x3fb8aa3b, v58
	v_mul_f32_e32 v59, 0x3fb8aa3b, v59
	v_exp_f32_e32 v58, v58
	v_exp_f32_e32 v62, v59
	v_lshlrev_b32_e32 v64, 16, v28
	v_and_b32_e32 v65, 0xffff0000, v28
	v_lshlrev_b32_e32 v28, 16, v29
	v_and_b32_e32 v29, 0xffff0000, v29
	v_pk_mul_f32 v[28:29], v[58:59], v[28:29] op_sel_hi:[0,1]
	v_pk_fma_f32 v[28:29], v[50:51], v[62:63], v[28:29] op_sel_hi:[1,0,1]
	v_lshlrev_b32_e32 v50, 16, v30
	v_and_b32_e32 v51, 0xffff0000, v30
	v_lshlrev_b32_e32 v30, 16, v31
	v_and_b32_e32 v31, 0xffff0000, v31
	v_pk_mul_f32 v[64:65], v[58:59], v[64:65] op_sel_hi:[0,1]
	v_pk_mul_f32 v[50:51], v[58:59], v[50:51] op_sel_hi:[0,1]
	v_pk_mul_f32 v[30:31], v[58:59], v[30:31] op_sel_hi:[0,1]
	v_pk_fma_f32 v[48:49], v[48:49], v[62:63], v[64:65] op_sel_hi:[1,0,1]
	v_pk_fma_f32 v[50:51], v[54:55], v[62:63], v[50:51] op_sel_hi:[1,0,1]
	v_pk_fma_f32 v[30:31], v[52:53], v[62:63], v[30:31] op_sel_hi:[1,0,1]
	v_lshl_add_u64 v[60:61], v[40:41], 0, s[12:13]
	v_cvt_pk_bf16_f32 v52, v48, v49
	v_cvt_pk_bf16_f32 v53, v28, v29
	v_cvt_pk_bf16_f32 v54, v50, v51
	v_cvt_pk_bf16_f32 v55, v30, v31
	global_store_dwordx4 v[60:61], v[52:55], off nt
	s_and_saveexec_b64 s[38:39], s[0:1]
	s_cbranch_execz .LBB0_389
	v_add_co_u32_e32 v52, vcc, 0x3f04000, v42
	s_nop 1
	v_addc_co_u32_e32 v53, vcc, 0, v43, vcc
	global_store_dword v[52:53], v32, off offset:4 nt
.LBB0_389:
	s_or_b64 exec, exec, s[38:39]
	global_load_dword v52, v[44:45], off offset:8
	global_load_dword v54, v[46:47], off offset:8
	v_add_f32_e32 v32, v32, v57
	v_max_f32_e32 v53, v56, v56
	v_max_f32_e32 v55, v32, v53
	v_sub_f32_e32 v32, v32, v55
	v_mul_f32_e32 v53, 0x3fb8aa3b, v32
	v_sub_f32_e32 v32, v56, v55
	v_mul_f32_e32 v32, 0x3fb8aa3b, v32
	v_exp_f32_e32 v32, v32
	v_exp_f32_e32 v56, v53
	v_lshlrev_b32_e32 v60, 16, v24
	v_and_b32_e32 v61, 0xffff0000, v24
	v_lshlrev_b32_e32 v24, 16, v25
	v_and_b32_e32 v25, 0xffff0000, v25
	v_pk_mul_f32 v[24:25], v[32:33], v[24:25] op_sel_hi:[0,1]
	v_pk_fma_f32 v[28:29], v[28:29], v[56:57], v[24:25] op_sel_hi:[1,0,1]
	v_lshlrev_b32_e32 v24, 16, v26
	v_and_b32_e32 v25, 0xffff0000, v26
	v_pk_mul_f32 v[24:25], v[32:33], v[24:25] op_sel_hi:[0,1]
	v_pk_fma_f32 v[50:51], v[50:51], v[56:57], v[24:25] op_sel_hi:[1,0,1]
	v_lshlrev_b32_e32 v24, 16, v27
	v_and_b32_e32 v25, 0xffff0000, v27
	v_pk_mul_f32 v[60:61], v[32:33], v[60:61] op_sel_hi:[0,1]
	v_pk_mul_f32 v[24:25], v[32:33], v[24:25] op_sel_hi:[0,1]
	v_pk_fma_f32 v[48:49], v[48:49], v[56:57], v[60:61] op_sel_hi:[1,0,1]
	v_pk_fma_f32 v[30:31], v[30:31], v[56:57], v[24:25] op_sel_hi:[1,0,1]
	v_lshl_add_u64 v[58:59], v[40:41], 0, s[14:15]
	v_cvt_pk_bf16_f32 v24, v48, v49
	v_cvt_pk_bf16_f32 v25, v28, v29
	v_cvt_pk_bf16_f32 v26, v50, v51
	v_cvt_pk_bf16_f32 v27, v30, v31
	global_store_dwordx4 v[58:59], v[24:27], off nt
	s_and_saveexec_b64 s[38:39], s[0:1]
	s_cbranch_execz .LBB0_391
	v_add_co_u32_e32 v24, vcc, 0x3f04000, v42
	s_nop 1
	v_addc_co_u32_e32 v25, vcc, 0, v43, vcc
	global_store_dword v[24:25], v55, off offset:8 nt
.LBB0_391:
	s_or_b64 exec, exec, s[38:39]
	global_load_dword v32, v[44:45], off offset:12
	global_load_dword v53, v[46:47], off offset:12
	s_waitcnt vmcnt(3)
	v_add_f32_e32 v24, v55, v54
	v_max_f32_e32 v25, v52, v52
	v_max_f32_e32 v54, v24, v25
	v_sub_f32_e32 v25, v52, v54
	v_sub_f32_e32 v24, v24, v54
	v_mul_f32_e32 v25, 0x3fb8aa3b, v25
	v_mul_f32_e32 v24, 0x3fb8aa3b, v24
	v_exp_f32_e32 v52, v25
	v_exp_f32_e32 v58, v24
	v_lshlrev_b32_e32 v24, 16, v20
	v_and_b32_e32 v25, 0xffff0000, v20
	v_lshlrev_b32_e32 v20, 16, v21
	v_and_b32_e32 v21, 0xffff0000, v21
	v_lshlrev_b32_e32 v26, 16, v22
	v_and_b32_e32 v27, 0xffff0000, v22
	v_lshlrev_b32_e32 v22, 16, v23
	v_and_b32_e32 v23, 0xffff0000, v23
	v_lshl_add_u64 v[56:57], v[40:41], 0, s[16:17]
	s_waitcnt vmcnt(0)
	v_pk_mul_f32 v[24:25], v[52:53], v[24:25] op_sel_hi:[0,1]
	v_pk_mul_f32 v[20:21], v[52:53], v[20:21] op_sel_hi:[0,1]
	v_pk_mul_f32 v[26:27], v[52:53], v[26:27] op_sel_hi:[0,1]
	v_pk_mul_f32 v[22:23], v[52:53], v[22:23] op_sel_hi:[0,1]
	v_pk_fma_f32 v[24:25], v[48:49], v[58:59], v[24:25] op_sel_hi:[1,0,1]
	v_pk_fma_f32 v[20:21], v[28:29], v[58:59], v[20:21] op_sel_hi:[1,0,1]
	v_pk_fma_f32 v[26:27], v[50:51], v[58:59], v[26:27] op_sel_hi:[1,0,1]
	v_pk_fma_f32 v[22:23], v[30:31], v[58:59], v[22:23] op_sel_hi:[1,0,1]
	v_cvt_pk_bf16_f32 v28, v24, v25
	v_cvt_pk_bf16_f32 v29, v20, v21
	v_cvt_pk_bf16_f32 v30, v26, v27
	v_cvt_pk_bf16_f32 v31, v22, v23
	global_store_dwordx4 v[56:57], v[28:31], off nt
	s_and_saveexec_b64 s[38:39], s[0:1]
	s_cbranch_execz .LBB0_393
	v_add_co_u32_e32 v28, vcc, 0x3f04000, v42
	s_nop 1
	v_addc_co_u32_e32 v29, vcc, 0, v43, vcc
	global_store_dword v[28:29], v54, off offset:12 nt
.LBB0_393:
	s_or_b64 exec, exec, s[38:39]
	global_load_dword v28, v[44:45], off offset:16
	global_load_dword v29, v[46:47], off offset:16
	v_add_f32_e32 v31, v54, v53
	v_max_f32_e32 v30, v32, v32
	v_max_f32_e32 v30, v31, v30
	v_sub_f32_e32 v31, v31, v30
	v_mul_f32_e32 v31, 0x3fb8aa3b, v31
	v_exp_f32_e32 v48, v31
	v_sub_f32_e32 v31, v32, v30
	v_mul_f32_e32 v31, 0x3fb8aa3b, v31
	v_exp_f32_e32 v32, v31
	v_lshlrev_b32_e32 v50, 16, v16
	v_and_b32_e32 v51, 0xffff0000, v16
	v_lshlrev_b32_e32 v52, 16, v17
	v_and_b32_e32 v53, 0xffff0000, v17
	v_lshlrev_b32_e32 v54, 16, v18
	v_and_b32_e32 v55, 0xffff0000, v18
	v_lshlrev_b32_e32 v58, 16, v19
	v_and_b32_e32 v59, 0xffff0000, v19
	v_pk_mul_f32 v[16:17], v[32:33], v[50:51] op_sel_hi:[0,1]
	v_pk_mul_f32 v[18:19], v[32:33], v[52:53] op_sel_hi:[0,1]
	v_pk_fma_f32 v[16:17], v[24:25], v[48:49], v[16:17] op_sel_hi:[1,0,1]
	v_pk_fma_f32 v[24:25], v[20:21], v[48:49], v[18:19] op_sel_hi:[1,0,1]
	v_pk_mul_f32 v[18:19], v[32:33], v[54:55] op_sel_hi:[0,1]
	v_pk_mul_f32 v[20:21], v[32:33], v[58:59] op_sel_hi:[0,1]
	v_pk_fma_f32 v[18:19], v[26:27], v[48:49], v[18:19] op_sel_hi:[1,0,1]
	v_pk_fma_f32 v[20:21], v[22:23], v[48:49], v[20:21] op_sel_hi:[1,0,1]
	v_lshl_add_u64 v[56:57], v[40:41], 0, s[18:19]
	v_cvt_pk_bf16_f32 v48, v16, v17
	v_cvt_pk_bf16_f32 v49, v24, v25
	v_cvt_pk_bf16_f32 v50, v18, v19
	v_cvt_pk_bf16_f32 v51, v20, v21
	global_store_dwordx4 v[56:57], v[48:51], off nt
	s_and_saveexec_b64 s[38:39], s[0:1]
	s_cbranch_execz .LBB0_395
	v_add_co_u32_e32 v22, vcc, 0x3f04000, v42
	s_nop 1
	v_addc_co_u32_e32 v23, vcc, 0, v43, vcc
	global_store_dword v[22:23], v30, off offset:16 nt
.LBB0_395:
	s_or_b64 exec, exec, s[38:39]
	global_load_dword v22, v[44:45], off offset:20
	global_load_dword v23, v[46:47], off offset:20
	s_waitcnt vmcnt(3)
	v_add_f32_e32 v27, v30, v29
	v_max_f32_e32 v26, v28, v28
	v_max_f32_e32 v26, v27, v26
	v_sub_f32_e32 v28, v28, v26
	v_sub_f32_e32 v27, v27, v26
	v_mul_f32_e32 v28, 0x3fb8aa3b, v28
	v_mul_f32_e32 v27, 0x3fb8aa3b, v27
	v_exp_f32_e32 v28, v28
	v_exp_f32_e32 v30, v27
	v_lshlrev_b32_e32 v50, 16, v12
	v_and_b32_e32 v51, 0xffff0000, v12
	v_lshlrev_b32_e32 v12, 16, v13
	v_and_b32_e32 v13, 0xffff0000, v13
	v_pk_mul_f32 v[12:13], v[28:29], v[12:13] op_sel_hi:[0,1]
	v_pk_fma_f32 v[12:13], v[24:25], v[30:31], v[12:13] op_sel_hi:[1,0,1]
	v_lshlrev_b32_e32 v24, 16, v14
	v_and_b32_e32 v25, 0xffff0000, v14
	v_lshlrev_b32_e32 v14, 16, v15
	v_and_b32_e32 v15, 0xffff0000, v15
	v_pk_mul_f32 v[50:51], v[28:29], v[50:51] op_sel_hi:[0,1]
	v_pk_mul_f32 v[24:25], v[28:29], v[24:25] op_sel_hi:[0,1]
	v_pk_mul_f32 v[14:15], v[28:29], v[14:15] op_sel_hi:[0,1]
	v_pk_fma_f32 v[16:17], v[16:17], v[30:31], v[50:51] op_sel_hi:[1,0,1]
	v_pk_fma_f32 v[18:19], v[18:19], v[30:31], v[24:25] op_sel_hi:[1,0,1]
	v_pk_fma_f32 v[14:15], v[20:21], v[30:31], v[14:15] op_sel_hi:[1,0,1]
	v_lshl_add_u64 v[48:49], v[40:41], 0, s[20:21]
	v_cvt_pk_bf16_f32 v28, v16, v17
	v_cvt_pk_bf16_f32 v29, v12, v13
	v_cvt_pk_bf16_f32 v30, v18, v19
	v_cvt_pk_bf16_f32 v31, v14, v15
	global_store_dwordx4 v[48:49], v[28:31], off nt
	s_and_saveexec_b64 s[38:39], s[0:1]
	s_cbranch_execz .LBB0_397
	v_add_co_u32_e32 v20, vcc, 0x3f04000, v42
	s_nop 1
	v_addc_co_u32_e32 v21, vcc, 0, v43, vcc
	global_store_dword v[20:21], v26, off offset:20 nt
.LBB0_397:
	s_or_b64 exec, exec, s[38:39]
	global_load_dword v20, v[44:45], off offset:24
	global_load_dword v21, v[46:47], off offset:24
	s_waitcnt vmcnt(3)
	v_add_f32_e32 v24, v26, v23
	v_max_f32_e32 v23, v22, v22
	v_max_f32_e32 v23, v24, v23
	v_sub_f32_e32 v22, v22, v23
	v_sub_f32_e32 v24, v24, v23
	v_mul_f32_e32 v22, 0x3fb8aa3b, v22
	v_mul_f32_e32 v24, 0x3fb8aa3b, v24
	v_exp_f32_e32 v22, v22
	v_exp_f32_e32 v24, v24
	v_lshlrev_b32_e32 v26, 16, v8
	v_and_b32_e32 v27, 0xffff0000, v8
	v_lshlrev_b32_e32 v8, 16, v9
	v_and_b32_e32 v9, 0xffff0000, v9
	v_pk_mul_f32 v[8:9], v[22:23], v[8:9] op_sel_hi:[0,1]
	v_pk_fma_f32 v[8:9], v[12:13], v[24:25], v[8:9] op_sel_hi:[1,0,1]
	v_lshlrev_b32_e32 v12, 16, v10
	v_and_b32_e32 v13, 0xffff0000, v10
	v_lshlrev_b32_e32 v10, 16, v11
	v_and_b32_e32 v11, 0xffff0000, v11
	v_pk_mul_f32 v[26:27], v[22:23], v[26:27] op_sel_hi:[0,1]
	v_pk_mul_f32 v[12:13], v[22:23], v[12:13] op_sel_hi:[0,1]
	v_pk_mul_f32 v[10:11], v[22:23], v[10:11] op_sel_hi:[0,1]
	v_pk_fma_f32 v[16:17], v[16:17], v[24:25], v[26:27] op_sel_hi:[1,0,1]
	v_pk_fma_f32 v[12:13], v[18:19], v[24:25], v[12:13] op_sel_hi:[1,0,1]
	v_pk_fma_f32 v[10:11], v[14:15], v[24:25], v[10:11] op_sel_hi:[1,0,1]
	v_lshl_add_u64 v[28:29], v[40:41], 0, s[24:25]
	v_cvt_pk_bf16_f32 v24, v16, v17
	v_cvt_pk_bf16_f32 v25, v8, v9
	v_cvt_pk_bf16_f32 v26, v12, v13
	v_cvt_pk_bf16_f32 v27, v10, v11
	global_store_dwordx4 v[28:29], v[24:27], off nt
	s_and_saveexec_b64 s[38:39], s[0:1]
	s_cbranch_execz .LBB0_399
	v_add_co_u32_e32 v14, vcc, 0x3f04000, v42
	s_nop 1
	v_addc_co_u32_e32 v15, vcc, 0, v43, vcc
	global_store_dword v[14:15], v23, off offset:24 nt
.LBB0_399:
	s_or_b64 exec, exec, s[38:39]
	global_load_dword v18, v[44:45], off offset:28
	global_load_dword v19, v[46:47], off offset:28
	s_waitcnt vmcnt(3)
	v_add_f32_e32 v14, v23, v21
	v_max_f32_e32 v15, v20, v20
	v_max_f32_e32 v21, v14, v15
	v_sub_f32_e32 v15, v20, v21
	v_sub_f32_e32 v14, v14, v21
	v_mul_f32_e32 v15, 0x3fb8aa3b, v15
	v_mul_f32_e32 v14, 0x3fb8aa3b, v14
	v_exp_f32_e32 v20, v15
	v_exp_f32_e32 v22, v14
	v_lshlrev_b32_e32 v14, 16, v4
	v_and_b32_e32 v15, 0xffff0000, v4
	v_lshlrev_b32_e32 v4, 16, v5
	v_and_b32_e32 v5, 0xffff0000, v5
	v_pk_mul_f32 v[14:15], v[20:21], v[14:15] op_sel_hi:[0,1]
	v_pk_mul_f32 v[4:5], v[20:21], v[4:5] op_sel_hi:[0,1]
	v_pk_fma_f32 v[16:17], v[16:17], v[22:23], v[14:15] op_sel_hi:[1,0,1]
	v_pk_fma_f32 v[14:15], v[8:9], v[22:23], v[4:5] op_sel_hi:[1,0,1]
	v_lshlrev_b32_e32 v4, 16, v6
	v_and_b32_e32 v5, 0xffff0000, v6
	v_pk_mul_f32 v[4:5], v[20:21], v[4:5] op_sel_hi:[0,1]
	v_pk_fma_f32 v[8:9], v[12:13], v[22:23], v[4:5] op_sel_hi:[1,0,1]
	v_lshlrev_b32_e32 v4, 16, v7
	v_and_b32_e32 v5, 0xffff0000, v7
	v_pk_mul_f32 v[4:5], v[20:21], v[4:5] op_sel_hi:[0,1]
	v_pk_fma_f32 v[4:5], v[10:11], v[22:23], v[4:5] op_sel_hi:[1,0,1]
	v_lshl_add_u64 v[24:25], v[40:41], 0, s[30:31]
	v_cvt_pk_bf16_f32 v10, v16, v17
	v_cvt_pk_bf16_f32 v11, v14, v15
	v_cvt_pk_bf16_f32 v12, v8, v9
	v_cvt_pk_bf16_f32 v13, v4, v5
	global_store_dwordx4 v[24:25], v[10:13], off nt
	s_and_saveexec_b64 s[38:39], s[0:1]
	s_cbranch_execz .LBB0_384
	v_add_co_u32_e32 v6, vcc, 0x3f04000, v42
	s_nop 1
	v_addc_co_u32_e32 v7, vcc, 0, v43, vcc
	global_store_dword v[6:7], v21, off offset:28 nt
	s_branch .LBB0_384

.LBB0_421:
	s_or_b64 exec, exec, s[54:55]
	s_add_u32 s54, s88, s8
	s_addc_u32 s55, s89, s9
	global_load_dword v81, v59, s[54:55]
	global_load_dword v82, v60, s[54:55]
	v_lshl_add_u64 v[48:49], v[44:45], 0, s[10:11]
	v_cvt_pk_bf16_f32 v84, v50, v51
	v_cvt_pk_bf16_f32 v85, v52, v53
	v_cvt_pk_bf16_f32 v86, v56, v57
	v_cvt_pk_bf16_f32 v87, v54, v55
	v_lshl_add_u64 v[88:89], v[46:47], 0, s[12:13]
	global_store_dwordx4 v[48:49], v[84:87], off nt
	v_cvt_pk_bf16_f32 v48, v75, s0
	global_store_short v[88:89], v48, off
	s_and_saveexec_b64 s[62:63], s[4:5]
	s_cbranch_execz .LBB0_423
	global_store_dword v61, v74, s[54:55] nt
.LBB0_423:
	s_or_b64 exec, exec, s[62:63]
	v_lshl_add_u64 v[48:49], s[88:89], 0, v[34:35]
	s_and_saveexec_b64 s[62:63], s[0:1]
	s_cbranch_execz .LBB0_425
	v_add_co_u32_e32 v84, vcc, 0x3f00000, v48
	s_nop 1
	v_addc_co_u32_e32 v85, vcc, 0, v49, vcc
	v_add_co_u32_e32 v86, vcc, 0x3f02000, v48
	s_nop 1
	v_addc_co_u32_e32 v87, vcc, 0, v49, vcc
	s_waitcnt vmcnt(2)
	v_mov_b32_e32 v79, v81
	v_mov_b32_e32 v80, v82
	v_add_co_u32_e32 v84, vcc, 0x3d00000, v42
	v_max_f32_e32 v83, v79, v79
	v_add_f32_e32 v80, v58, v80
	v_max_f32_e32 v58, v80, v83
	v_sub_f32_e32 v80, v80, v58
	v_sub_f32_e32 v79, v79, v58
	v_mul_f32_e32 v80, 0x3fb8aa3b, v80
	v_mul_f32_e32 v79, 0x3fb8aa3b, v79
	v_exp_f32_e32 v86, v80
	v_exp_f32_e32 v87, v79
	v_addc_co_u32_e32 v85, vcc, 0, v43, vcc
	global_store_dword v[84:85], v40, off nt
	v_pk_mul_f32 v[40:41], v[40:41], v[86:87]
	s_nop 0
	v_add_f32_e32 v40, v40, v41
.LBB0_425:
	s_or_b64 exec, exec, s[62:63]
	global_load_dword v79, v59, s[54:55] offset:4
	global_load_dword v80, v60, s[54:55] offset:4
	s_waitcnt vmcnt(0)
	v_add_f32_e32 v41, v74, v82
	v_max_f32_e32 v74, v81, v81
	v_max_f32_e32 v74, v41, v74
	v_sub_f32_e32 v81, v81, v74
	v_sub_f32_e32 v41, v41, v74
	v_mul_f32_e32 v81, 0x3fb8aa3b, v81
	v_mul_f32_e32 v41, 0x3fb8aa3b, v41
	v_exp_f32_e32 v82, v81
	v_exp_f32_e32 v84, v41
	v_lshlrev_b32_e32 v90, 16, v28
	v_and_b32_e32 v91, 0xffff0000, v28
	v_lshlrev_b32_e32 v28, 16, v29
	v_and_b32_e32 v29, 0xffff0000, v29
	v_pk_mul_f32 v[28:29], v[82:83], v[28:29] op_sel_hi:[0,1]
	v_pk_fma_f32 v[28:29], v[52:53], v[84:85], v[28:29] op_sel_hi:[1,0,1]
	v_lshlrev_b32_e32 v52, 16, v30
	v_and_b32_e32 v53, 0xffff0000, v30
	v_lshlrev_b32_e32 v30, 16, v31
	v_and_b32_e32 v31, 0xffff0000, v31
	v_pk_mul_f32 v[30:31], v[82:83], v[30:31] op_sel_hi:[0,1]
	v_lshlrev_b32_e32 v41, 16, v78
	v_pk_mul_f32 v[90:91], v[82:83], v[90:91] op_sel_hi:[0,1]
	v_pk_mul_f32 v[52:53], v[82:83], v[52:53] op_sel_hi:[0,1]
	v_pk_fma_f32 v[30:31], v[54:55], v[84:85], v[30:31] op_sel_hi:[1,0,1]
	v_mul_f32_e32 v54, v82, v41
	v_pk_fma_f32 v[50:51], v[50:51], v[84:85], v[90:91] op_sel_hi:[1,0,1]
	v_pk_fma_f32 v[52:53], v[56:57], v[84:85], v[52:53] op_sel_hi:[1,0,1]
	v_fmac_f32_e32 v54, v75, v84
	v_lshl_add_u64 v[86:87], v[44:45], 0, s[14:15]
	v_lshl_add_u64 v[88:89], v[46:47], 0, s[16:17]
	v_cvt_pk_bf16_f32 v82, v50, v51
	v_cvt_pk_bf16_f32 v83, v28, v29
	v_cvt_pk_bf16_f32 v84, v52, v53
	v_cvt_pk_bf16_f32 v85, v30, v31
	v_cvt_pk_bf16_f32 v41, v54, s0
	global_store_dwordx4 v[86:87], v[82:85], off nt
	global_store_short v[88:89], v41, off
	s_and_saveexec_b64 s[62:63], s[4:5]
	s_cbranch_execz .LBB0_427
	global_store_dword v61, v74, s[54:55] offset:4 nt
.LBB0_427:
	s_or_b64 exec, exec, s[62:63]
	s_and_saveexec_b64 s[62:63], s[0:1]
	s_cbranch_execz .LBB0_429
	v_add_co_u32_e32 v56, vcc, 0x3f00000, v48
	s_nop 1
	v_addc_co_u32_e32 v57, vcc, 0, v49, vcc
	v_add_co_u32_e32 v82, vcc, 0x3f02000, v48
	s_nop 1
	v_addc_co_u32_e32 v83, vcc, 0, v49, vcc
	s_waitcnt vmcnt(2)
	v_mov_b32_e32 v41, v79
	v_mov_b32_e32 v55, v80
	v_add_co_u32_e32 v56, vcc, 0x3d00000, v42
	v_max_f32_e32 v57, v41, v41
	v_add_f32_e32 v55, v58, v55
	v_max_f32_e32 v58, v55, v57
	v_sub_f32_e32 v55, v55, v58
	v_sub_f32_e32 v41, v41, v58
	v_mul_f32_e32 v55, 0x3fb8aa3b, v55
	v_mul_f32_e32 v41, 0x3fb8aa3b, v41
	v_exp_f32_e32 v82, v55
	v_exp_f32_e32 v83, v41
	v_addc_co_u32_e32 v57, vcc, 0, v43, vcc
	v_mov_b32_e32 v41, v77
	global_store_dword v[56:57], v40, off offset:768 nt
	v_pk_mul_f32 v[40:41], v[40:41], v[82:83]
	s_nop 0
	v_add_f32_e32 v40, v40, v41
.LBB0_429:
	s_or_b64 exec, exec, s[62:63]
	global_load_dword v55, v59, s[54:55] offset:8
	global_load_dword v56, v60, s[54:55] offset:8
	v_add_f32_e32 v41, v74, v80
	v_max_f32_e32 v57, v79, v79
	v_max_f32_e32 v75, v41, v57
	v_sub_f32_e32 v57, v79, v75
	v_sub_f32_e32 v41, v41, v75
	v_mul_f32_e32 v57, 0x3fb8aa3b, v57
	v_mul_f32_e32 v41, 0x3fb8aa3b, v41
	v_exp_f32_e32 v74, v57
	v_exp_f32_e32 v78, v41
	v_lshlrev_b32_e32 v80, 16, v24
	v_and_b32_e32 v81, 0xffff0000, v24
	v_lshlrev_b32_e32 v24, 16, v25
	v_and_b32_e32 v25, 0xffff0000, v25
	v_pk_mul_f32 v[24:25], v[74:75], v[24:25] op_sel_hi:[0,1]
	v_pk_fma_f32 v[28:29], v[28:29], v[78:79], v[24:25] op_sel_hi:[1,0,1]
	v_lshlrev_b32_e32 v24, 16, v26
	v_and_b32_e32 v25, 0xffff0000, v26
	v_pk_mul_f32 v[24:25], v[74:75], v[24:25] op_sel_hi:[0,1]
	v_pk_fma_f32 v[52:53], v[52:53], v[78:79], v[24:25] op_sel_hi:[1,0,1]
	v_lshlrev_b32_e32 v24, 16, v27
	v_and_b32_e32 v25, 0xffff0000, v27
	v_pk_mul_f32 v[24:25], v[74:75], v[24:25] op_sel_hi:[0,1]
	v_pk_mul_f32 v[80:81], v[74:75], v[80:81] op_sel_hi:[0,1]
	v_pk_fma_f32 v[30:31], v[30:31], v[78:79], v[24:25] op_sel_hi:[1,0,1]
	v_lshlrev_b32_e32 v24, 16, v76
	v_pk_fma_f32 v[50:51], v[50:51], v[78:79], v[80:81] op_sel_hi:[1,0,1]
	v_mul_f32_e32 v74, v74, v24
	v_lshl_add_u64 v[82:83], v[44:45], 0, s[18:19]
	v_fmac_f32_e32 v74, v54, v78
	v_cvt_pk_bf16_f32 v24, v50, v51
	v_cvt_pk_bf16_f32 v25, v28, v29
	v_cvt_pk_bf16_f32 v26, v52, v53
	v_cvt_pk_bf16_f32 v27, v30, v31
	v_lshl_add_u64 v[84:85], v[46:47], 0, s[20:21]
	global_store_dwordx4 v[82:83], v[24:27], off nt
	s_nop 1
	v_cvt_pk_bf16_f32 v24, v74, s0
	global_store_short v[84:85], v24, off
	s_and_saveexec_b64 s[62:63], s[4:5]
	s_cbranch_execz .LBB0_431
	global_store_dword v61, v75, s[54:55] offset:8 nt
.LBB0_431:
	s_or_b64 exec, exec, s[62:63]
	s_and_saveexec_b64 s[62:63], s[0:1]
	s_cbranch_execz .LBB0_433
	v_add_co_u32_e32 v24, vcc, 0x3f00000, v48
	v_mov_b32_e32 v41, v73
	s_nop 0
	v_addc_co_u32_e32 v25, vcc, 0, v49, vcc
	v_add_co_u32_e32 v26, vcc, 0x3f02000, v48
	s_nop 1
	v_addc_co_u32_e32 v27, vcc, 0, v49, vcc
	s_waitcnt vmcnt(2)
	v_mov_b32_e32 v25, v55
	s_nop 0
	v_mov_b32_e32 v26, v56
	v_add_co_u32_e32 v24, vcc, 0x3d00000, v42
	v_max_f32_e32 v27, v25, v25
	v_add_f32_e32 v26, v58, v26
	v_max_f32_e32 v58, v26, v27
	v_sub_f32_e32 v26, v26, v58
	v_sub_f32_e32 v25, v25, v58
	v_mul_f32_e32 v26, 0x3fb8aa3b, v26
	v_mul_f32_e32 v25, 0x3fb8aa3b, v25
	v_exp_f32_e32 v26, v26
	v_exp_f32_e32 v27, v25
	v_addc_co_u32_e32 v25, vcc, 0, v43, vcc
	global_store_dword v[24:25], v40, off offset:1536 nt
	v_pk_mul_f32 v[24:25], v[40:41], v[26:27]
	s_nop 0
	v_add_f32_e32 v40, v24, v25
.LBB0_433:
	s_or_b64 exec, exec, s[62:63]
	global_load_dword v54, v59, s[54:55] offset:12
	global_load_dword v57, v60, s[54:55] offset:12
	s_waitcnt vmcnt(4)
	v_add_f32_e32 v24, v75, v56
	v_max_f32_e32 v25, v55, v55
	v_max_f32_e32 v56, v24, v25
	v_sub_f32_e32 v25, v55, v56
	v_sub_f32_e32 v24, v24, v56
	v_mul_f32_e32 v25, 0x3fb8aa3b, v25
	v_mul_f32_e32 v24, 0x3fb8aa3b, v24
	v_exp_f32_e32 v80, v25
	v_exp_f32_e32 v82, v24
	v_lshlrev_b32_e32 v24, 16, v20
	v_and_b32_e32 v25, 0xffff0000, v20
	v_lshlrev_b32_e32 v20, 16, v21
	v_and_b32_e32 v21, 0xffff0000, v21
	v_pk_mul_f32 v[20:21], v[80:81], v[20:21] op_sel_hi:[0,1]
	v_lshlrev_b32_e32 v26, 16, v22
	v_and_b32_e32 v27, 0xffff0000, v22
	v_lshlrev_b32_e32 v22, 16, v23
	v_and_b32_e32 v23, 0xffff0000, v23
	v_pk_fma_f32 v[20:21], v[28:29], v[82:83], v[20:21] op_sel_hi:[1,0,1]
	v_pk_mul_f32 v[22:23], v[80:81], v[22:23] op_sel_hi:[0,1]
	v_lshlrev_b32_e32 v28, 16, v72
	v_pk_mul_f32 v[24:25], v[80:81], v[24:25] op_sel_hi:[0,1]
	v_pk_mul_f32 v[26:27], v[80:81], v[26:27] op_sel_hi:[0,1]
	v_pk_fma_f32 v[22:23], v[30:31], v[82:83], v[22:23] op_sel_hi:[1,0,1]
	v_mul_f32_e32 v30, v80, v28
	v_pk_fma_f32 v[24:25], v[50:51], v[82:83], v[24:25] op_sel_hi:[1,0,1]
	v_pk_fma_f32 v[26:27], v[52:53], v[82:83], v[26:27] op_sel_hi:[1,0,1]
	v_fmac_f32_e32 v30, v74, v82
	v_lshl_add_u64 v[76:77], v[44:45], 0, s[24:25]
	v_lshl_add_u64 v[78:79], v[46:47], 0, s[30:31]
	v_cvt_pk_bf16_f32 v50, v24, v25
	v_cvt_pk_bf16_f32 v51, v20, v21
	v_cvt_pk_bf16_f32 v52, v26, v27
	v_cvt_pk_bf16_f32 v53, v22, v23
	v_cvt_pk_bf16_f32 v28, v30, s0
	global_store_dwordx4 v[76:77], v[50:53], off nt
	global_store_short v[78:79], v28, off
	s_and_saveexec_b64 s[62:63], s[4:5]
	s_cbranch_execz .LBB0_435
	global_store_dword v61, v56, s[54:55] offset:12 nt
.LBB0_435:
	s_or_b64 exec, exec, s[62:63]
	s_and_saveexec_b64 s[62:63], s[0:1]
	s_cbranch_execz .LBB0_437
	v_add_co_u32_e32 v28, vcc, 0x3f00000, v48
	s_nop 1
	v_addc_co_u32_e32 v29, vcc, 0, v49, vcc
	v_add_co_u32_e32 v50, vcc, 0x3f02000, v48
	s_nop 1
	v_addc_co_u32_e32 v51, vcc, 0, v49, vcc
	s_waitcnt vmcnt(2)
	v_mov_b32_e32 v29, v54
	s_nop 0
	v_mov_b32_e32 v31, v57
	v_add_co_u32_e32 v28, vcc, 0x3d00000, v42
	v_max_f32_e32 v41, v29, v29
	v_add_f32_e32 v31, v58, v31
	v_max_f32_e32 v58, v31, v41
	v_sub_f32_e32 v31, v31, v58
	v_sub_f32_e32 v29, v29, v58
	v_mul_f32_e32 v31, 0x3fb8aa3b, v31
	v_mul_f32_e32 v29, 0x3fb8aa3b, v29
	v_exp_f32_e32 v50, v31
	v_exp_f32_e32 v51, v29
	v_addc_co_u32_e32 v29, vcc, 0, v43, vcc
	v_mov_b32_e32 v41, v71
	global_store_dword v[28:29], v40, off offset:2304 nt
	v_pk_mul_f32 v[28:29], v[40:41], v[50:51]
	s_nop 0
	v_add_f32_e32 v40, v28, v29
.LBB0_437:
	s_or_b64 exec, exec, s[62:63]
	global_load_dword v28, v59, s[54:55] offset:16
	global_load_dword v29, v60, s[54:55] offset:16
	s_waitcnt vmcnt(4)
	v_add_f32_e32 v41, v56, v57
	v_max_f32_e32 v31, v54, v54
	v_max_f32_e32 v31, v41, v31
	v_sub_f32_e32 v41, v41, v31
	v_mul_f32_e32 v41, 0x3fb8aa3b, v41
	v_exp_f32_e32 v50, v41
	v_sub_f32_e32 v41, v54, v31
	v_mul_f32_e32 v41, 0x3fb8aa3b, v41
	v_exp_f32_e32 v52, v41
	v_lshlrev_b32_e32 v54, 16, v16
	v_and_b32_e32 v55, 0xffff0000, v16
	v_lshlrev_b32_e32 v16, 16, v17
	v_and_b32_e32 v17, 0xffff0000, v17
	v_lshlrev_b32_e32 v56, 16, v18
	v_and_b32_e32 v57, 0xffff0000, v18
	v_lshlrev_b32_e32 v76, 16, v19
	v_and_b32_e32 v77, 0xffff0000, v19
	v_pk_mul_f32 v[18:19], v[52:53], v[54:55] op_sel_hi:[0,1]
	v_pk_mul_f32 v[16:17], v[52:53], v[16:17] op_sel_hi:[0,1]
	v_pk_fma_f32 v[18:19], v[24:25], v[50:51], v[18:19] op_sel_hi:[1,0,1]
	v_pk_fma_f32 v[24:25], v[20:21], v[50:51], v[16:17] op_sel_hi:[1,0,1]
	v_pk_mul_f32 v[16:17], v[52:53], v[56:57] op_sel_hi:[0,1]
	v_pk_fma_f32 v[20:21], v[26:27], v[50:51], v[16:17] op_sel_hi:[1,0,1]
	v_pk_mul_f32 v[16:17], v[52:53], v[76:77] op_sel_hi:[0,1]
	v_pk_fma_f32 v[16:17], v[22:23], v[50:51], v[16:17] op_sel_hi:[1,0,1]
	v_lshlrev_b32_e32 v22, 16, v70
	v_mul_f32_e32 v23, v52, v22
	v_fmac_f32_e32 v23, v30, v50
	v_lshl_add_u64 v[72:73], v[44:45], 0, s[34:35]
	v_lshl_add_u64 v[74:75], v[46:47], 0, s[36:37]
	v_cvt_pk_bf16_f32 v50, v18, v19
	v_cvt_pk_bf16_f32 v51, v24, v25
	v_cvt_pk_bf16_f32 v52, v20, v21
	v_cvt_pk_bf16_f32 v53, v16, v17
	v_cvt_pk_bf16_f32 v22, v23, s0
	global_store_dwordx4 v[72:73], v[50:53], off nt
	global_store_short v[74:75], v22, off
	s_and_saveexec_b64 s[62:63], s[4:5]
	s_cbranch_execz .LBB0_439
	global_store_dword v61, v31, s[54:55] offset:16 nt
.LBB0_439:
	s_or_b64 exec, exec, s[62:63]
	s_and_saveexec_b64 s[62:63], s[0:1]
	s_cbranch_execz .LBB0_441
	v_add_co_u32_e32 v26, vcc, 0x3f00000, v48
	v_mov_b32_e32 v41, v69
	s_nop 0
	v_addc_co_u32_e32 v27, vcc, 0, v49, vcc
	v_add_co_u32_e32 v50, vcc, 0x3f02000, v48
	s_nop 1
	v_addc_co_u32_e32 v51, vcc, 0, v49, vcc
	s_waitcnt vmcnt(2)
	v_mov_b32_e32 v22, v28
	s_nop 0
	v_mov_b32_e32 v27, v29
	v_add_co_u32_e32 v26, vcc, 0x3d00000, v42
	v_max_f32_e32 v30, v22, v22
	v_add_f32_e32 v27, v58, v27
	v_max_f32_e32 v58, v27, v30
	v_sub_f32_e32 v27, v27, v58
	v_sub_f32_e32 v22, v22, v58
	v_mul_f32_e32 v27, 0x3fb8aa3b, v27
	v_mul_f32_e32 v22, 0x3fb8aa3b, v22
	v_exp_f32_e32 v50, v27
	v_exp_f32_e32 v51, v22
	v_addc_co_u32_e32 v27, vcc, 0, v43, vcc
	global_store_dword v[26:27], v40, off offset:3072 nt
	v_pk_mul_f32 v[26:27], v[40:41], v[50:51]
	s_nop 0
	v_add_f32_e32 v40, v26, v27
.LBB0_441:
	s_or_b64 exec, exec, s[62:63]
	global_load_dword v22, v59, s[54:55] offset:20
	global_load_dword v26, v60, s[54:55] offset:20
	s_waitcnt vmcnt(4)
	v_add_f32_e32 v29, v31, v29
	v_max_f32_e32 v27, v28, v28
	v_max_f32_e32 v27, v29, v27
	v_sub_f32_e32 v28, v28, v27
	v_sub_f32_e32 v29, v29, v27
	v_mul_f32_e32 v28, 0x3fb8aa3b, v28
	v_mul_f32_e32 v29, 0x3fb8aa3b, v29
	v_exp_f32_e32 v28, v28
	v_exp_f32_e32 v30, v29
	v_lshlrev_b32_e32 v54, 16, v12
	v_and_b32_e32 v55, 0xffff0000, v12
	v_lshlrev_b32_e32 v12, 16, v13
	v_and_b32_e32 v13, 0xffff0000, v13
	v_pk_mul_f32 v[12:13], v[28:29], v[12:13] op_sel_hi:[0,1]
	v_pk_fma_f32 v[12:13], v[24:25], v[30:31], v[12:13] op_sel_hi:[1,0,1]
	v_lshlrev_b32_e32 v24, 16, v14
	v_and_b32_e32 v25, 0xffff0000, v14
	v_lshlrev_b32_e32 v14, 16, v15
	v_and_b32_e32 v15, 0xffff0000, v15
	v_pk_mul_f32 v[14:15], v[28:29], v[14:15] op_sel_hi:[0,1]
	v_pk_mul_f32 v[24:25], v[28:29], v[24:25] op_sel_hi:[0,1]
	v_pk_fma_f32 v[14:15], v[16:17], v[30:31], v[14:15] op_sel_hi:[1,0,1]
	v_lshlrev_b32_e32 v16, 16, v68
	v_pk_mul_f32 v[54:55], v[28:29], v[54:55] op_sel_hi:[0,1]
	v_pk_fma_f32 v[20:21], v[20:21], v[30:31], v[24:25] op_sel_hi:[1,0,1]
	v_mul_f32_e32 v25, v28, v16
	v_pk_fma_f32 v[18:19], v[18:19], v[30:31], v[54:55] op_sel_hi:[1,0,1]
	v_fmac_f32_e32 v25, v23, v30
	v_lshl_add_u64 v[50:51], v[44:45], 0, s[38:39]
	v_lshl_add_u64 v[52:53], v[46:47], 0, s[40:41]
	v_cvt_pk_bf16_f32 v28, v18, v19
	v_cvt_pk_bf16_f32 v29, v12, v13
	v_cvt_pk_bf16_f32 v30, v20, v21
	v_cvt_pk_bf16_f32 v31, v14, v15
	v_cvt_pk_bf16_f32 v16, v25, s0
	global_store_dwordx4 v[50:51], v[28:31], off nt
	global_store_short v[52:53], v16, off
	s_and_saveexec_b64 s[62:63], s[4:5]
	s_cbranch_execz .LBB0_443
	global_store_dword v61, v27, s[54:55] offset:20 nt
.LBB0_443:
	s_or_b64 exec, exec, s[62:63]
	s_and_saveexec_b64 s[62:63], s[0:1]
	s_cbranch_execz .LBB0_445
	v_add_co_u32_e32 v16, vcc, 0x3f00000, v48
	v_mov_b32_e32 v41, v67
	s_nop 0
	v_addc_co_u32_e32 v17, vcc, 0, v49, vcc
	v_add_co_u32_e32 v28, vcc, 0x3f02000, v48
	s_nop 1
	v_addc_co_u32_e32 v29, vcc, 0, v49, vcc
	s_waitcnt vmcnt(2)
	v_mov_b32_e32 v17, v22
	s_nop 0
	v_mov_b32_e32 v23, v26
	v_add_co_u32_e32 v16, vcc, 0x3d00000, v42
	v_max_f32_e32 v24, v17, v17
	v_add_f32_e32 v23, v58, v23
	v_max_f32_e32 v58, v23, v24
	v_sub_f32_e32 v23, v23, v58
	v_sub_f32_e32 v17, v17, v58
	v_mul_f32_e32 v23, 0x3fb8aa3b, v23
	v_mul_f32_e32 v17, 0x3fb8aa3b, v17
	v_exp_f32_e32 v28, v23
	v_exp_f32_e32 v29, v17
	v_addc_co_u32_e32 v17, vcc, 0, v43, vcc
	global_store_dword v[16:17], v40, off offset:3840 nt
	v_pk_mul_f32 v[16:17], v[40:41], v[28:29]
	s_nop 0
	v_add_f32_e32 v40, v16, v17
.LBB0_445:
	s_or_b64 exec, exec, s[62:63]
	global_load_dword v23, v59, s[54:55] offset:24
	global_load_dword v24, v60, s[54:55] offset:24
	s_waitcnt vmcnt(4)
	v_add_f32_e32 v16, v27, v26
	v_max_f32_e32 v17, v22, v22
	v_max_f32_e32 v26, v16, v17
	v_sub_f32_e32 v17, v22, v26
	v_sub_f32_e32 v16, v16, v26
	v_mul_f32_e32 v17, 0x3fb8aa3b, v17
	v_mul_f32_e32 v16, 0x3fb8aa3b, v16
	v_exp_f32_e32 v22, v17
	v_exp_f32_e32 v28, v16
	v_lshlrev_b32_e32 v16, 16, v8
	v_and_b32_e32 v17, 0xffff0000, v8
	v_lshlrev_b32_e32 v8, 16, v9
	v_and_b32_e32 v9, 0xffff0000, v9
	v_lshl_add_u64 v[50:51], v[44:45], 0, s[42:43]
	v_lshl_add_u64 v[52:53], v[46:47], 0, s[44:45]
	s_waitcnt vmcnt(1)
	v_pk_mul_f32 v[8:9], v[22:23], v[8:9] op_sel_hi:[0,1]
	v_pk_fma_f32 v[8:9], v[12:13], v[28:29], v[8:9] op_sel_hi:[1,0,1]
	v_lshlrev_b32_e32 v12, 16, v10
	v_and_b32_e32 v13, 0xffff0000, v10
	v_lshlrev_b32_e32 v10, 16, v11
	v_and_b32_e32 v11, 0xffff0000, v11
	v_pk_mul_f32 v[10:11], v[22:23], v[10:11] op_sel_hi:[0,1]
	v_pk_mul_f32 v[16:17], v[22:23], v[16:17] op_sel_hi:[0,1]
	v_pk_fma_f32 v[10:11], v[14:15], v[28:29], v[10:11] op_sel_hi:[1,0,1]
	v_lshlrev_b32_e32 v14, 16, v66
	v_pk_fma_f32 v[16:17], v[18:19], v[28:29], v[16:17] op_sel_hi:[1,0,1]
	v_pk_mul_f32 v[12:13], v[22:23], v[12:13] op_sel_hi:[0,1]
	v_mul_f32_e32 v18, v22, v14
	v_pk_fma_f32 v[12:13], v[20:21], v[28:29], v[12:13] op_sel_hi:[1,0,1]
	v_fmac_f32_e32 v18, v25, v28
	v_cvt_pk_bf16_f32 v28, v16, v17
	v_cvt_pk_bf16_f32 v29, v8, v9
	v_cvt_pk_bf16_f32 v30, v12, v13
	v_cvt_pk_bf16_f32 v31, v10, v11
	v_cvt_pk_bf16_f32 v14, v18, s0
	global_store_dwordx4 v[50:51], v[28:31], off nt
	global_store_short v[52:53], v14, off
	s_and_saveexec_b64 s[62:63], s[4:5]
	s_cbranch_execz .LBB0_447
	global_store_dword v61, v26, s[54:55] offset:24 nt
.LBB0_447:
	s_or_b64 exec, exec, s[62:63]
	s_and_saveexec_b64 s[62:63], s[0:1]
	s_cbranch_execz .LBB0_449
	v_add_co_u32_e32 v14, vcc, 0x3f00000, v48
	v_mov_b32_e32 v41, v65
	s_nop 0
	v_addc_co_u32_e32 v15, vcc, 0, v49, vcc
	v_add_co_u32_e32 v20, vcc, 0x3f02000, v48
	s_nop 1
	v_addc_co_u32_e32 v21, vcc, 0, v49, vcc
	s_waitcnt vmcnt(2)
	v_mov_b32_e32 v15, v23
	s_nop 0
	v_mov_b32_e32 v19, v24
	v_add_co_u32_e32 v14, vcc, 0x3d01000, v42
	v_max_f32_e32 v20, v15, v15
	v_add_f32_e32 v19, v58, v19
	v_max_f32_e32 v58, v19, v20
	v_sub_f32_e32 v19, v19, v58
	v_sub_f32_e32 v15, v15, v58
	v_mul_f32_e32 v19, 0x3fb8aa3b, v19
	v_mul_f32_e32 v15, 0x3fb8aa3b, v15
	v_exp_f32_e32 v20, v19
	v_exp_f32_e32 v21, v15
	v_addc_co_u32_e32 v15, vcc, 0, v43, vcc
	global_store_dword v[14:15], v40, off offset:512 nt
	v_pk_mul_f32 v[14:15], v[40:41], v[20:21]
	s_nop 0
	v_add_f32_e32 v40, v14, v15
.LBB0_449:
	s_or_b64 exec, exec, s[62:63]
	global_load_dword v19, v59, s[54:55] offset:28
	global_load_dword v20, v60, s[54:55] offset:28
	s_waitcnt vmcnt(4)
	v_add_f32_e32 v14, v26, v24
	v_max_f32_e32 v15, v23, v23
	v_max_f32_e32 v21, v14, v15
	v_sub_f32_e32 v15, v23, v21
	v_sub_f32_e32 v14, v14, v21
	v_mul_f32_e32 v15, 0x3fb8aa3b, v15
	v_mul_f32_e32 v14, 0x3fb8aa3b, v14
	v_exp_f32_e32 v22, v15
	v_exp_f32_e32 v24, v14
	v_lshlrev_b32_e32 v14, 16, v4
	v_and_b32_e32 v15, 0xffff0000, v4
	v_lshlrev_b32_e32 v4, 16, v5
	v_and_b32_e32 v5, 0xffff0000, v5
	v_pk_mul_f32 v[14:15], v[22:23], v[14:15] op_sel_hi:[0,1]
	v_pk_mul_f32 v[4:5], v[22:23], v[4:5] op_sel_hi:[0,1]
	v_pk_fma_f32 v[16:17], v[16:17], v[24:25], v[14:15] op_sel_hi:[1,0,1]
	v_pk_fma_f32 v[14:15], v[8:9], v[24:25], v[4:5] op_sel_hi:[1,0,1]
	v_lshlrev_b32_e32 v4, 16, v6
	v_and_b32_e32 v5, 0xffff0000, v6
	v_pk_mul_f32 v[4:5], v[22:23], v[4:5] op_sel_hi:[0,1]
	v_pk_fma_f32 v[8:9], v[12:13], v[24:25], v[4:5] op_sel_hi:[1,0,1]
	v_lshlrev_b32_e32 v4, 16, v7
	v_and_b32_e32 v5, 0xffff0000, v7
	v_lshlrev_b32_e32 v6, 16, v64
	v_pk_mul_f32 v[4:5], v[22:23], v[4:5] op_sel_hi:[0,1]
	v_mul_f32_e32 v6, v22, v6
	v_pk_fma_f32 v[4:5], v[10:11], v[24:25], v[4:5] op_sel_hi:[1,0,1]
	v_fmac_f32_e32 v6, v18, v24
	v_lshl_add_u64 v[28:29], v[44:45], 0, s[46:47]
	v_lshl_add_u64 v[30:31], v[46:47], 0, s[48:49]
	v_cvt_pk_bf16_f32 v10, v16, v17
	v_cvt_pk_bf16_f32 v11, v14, v15
	v_cvt_pk_bf16_f32 v12, v8, v9
	v_cvt_pk_bf16_f32 v13, v4, v5
	v_cvt_pk_bf16_f32 v7, v6, s0
	global_store_dwordx4 v[28:29], v[10:13], off nt
	global_store_short v[30:31], v7, off
	s_and_saveexec_b64 s[62:63], s[4:5]
	s_cbranch_execz .LBB0_451
	global_store_dword v61, v21, s[54:55] offset:28 nt
.LBB0_451:
	s_or_b64 exec, exec, s[62:63]
	s_and_saveexec_b64 s[54:55], s[0:1]
	s_cbranch_execz .LBB0_404
	v_add_co_u32_e32 v10, vcc, 0x3f00000, v48
	v_mov_b32_e32 v41, v63
	s_nop 0
	v_addc_co_u32_e32 v11, vcc, 0, v49, vcc
	v_add_co_u32_e32 v12, vcc, 0x3f02000, v48
	s_nop 1
	v_addc_co_u32_e32 v13, vcc, 0, v49, vcc
	s_waitcnt vmcnt(2)
	v_mov_b32_e32 v7, v19
	s_nop 0
	v_mov_b32_e32 v11, v20
	v_add_co_u32_e32 v10, vcc, 0x3d01000, v42
	v_max_f32_e32 v12, v7, v7
	v_add_f32_e32 v11, v58, v11
	v_max_f32_e32 v58, v11, v12
	v_sub_f32_e32 v11, v11, v58
	v_sub_f32_e32 v7, v7, v58
	v_mul_f32_e32 v11, 0x3fb8aa3b, v11
	v_mul_f32_e32 v7, 0x3fb8aa3b, v7
	v_exp_f32_e32 v12, v11
	v_exp_f32_e32 v13, v7
	v_addc_co_u32_e32 v11, vcc, 0, v43, vcc
	global_store_dword v[10:11], v40, off offset:1280 nt
	v_pk_mul_f32 v[10:11], v[40:41], v[12:13]
	s_nop 0
	v_add_f32_e32 v40, v10, v11
	s_branch .LBB0_404
